# baseline (speedup 1.0000x reference)
.LBB0_22:
	v_and_b32_e32 v6, 0x1800, v11
	v_add_u32_e32 v6, 0xfffff800, v6
	v_cmp_gt_u32_e32 vcc, s0, v11
	s_nop 1
	v_cndmask_b32_e64 v6, v6, 0, vcc
	v_cndmask_b32_e32 v13, v5, v8, vcc
	v_cndmask_b32_e32 v12, v9, v10, vcc
	v_and_or_b32 v6, v11, s1, v6
	v_lshl_add_u64 v[12:13], v[6:7], 2, v[12:13]
	global_load_dword v6, v[12:13], off
	v_add_u32_e32 v12, 0x200, v11
	v_cmp_lt_u32_e32 vcc, s2, v11
	v_mov_b32_e32 v11, v12
	s_or_b64 s[4:5], vcc, s[4:5]
	s_waitcnt vmcnt(0)
	v_mul_f32_e32 v12, 0xbfb8aa3b, v6
	v_exp_f32_e32 v12, v12
	s_nop 0
	v_add_f32_e32 v12, 1.0, v12
	v_div_scale_f32 v13, s[6:7], v12, v12, v6
	v_rcp_f32_e32 v14, v13
	v_div_scale_f32 v15, vcc, v6, v12, v6
	v_fma_f32 v16, -v13, v14, 1.0
	v_fmac_f32_e32 v14, v16, v14
	v_mul_f32_e32 v16, v15, v14
	v_fma_f32 v17, -v13, v16, v15
	v_fmac_f32_e32 v16, v17, v14
	v_fma_f32 v13, -v13, v16, v15
	v_div_fmas_f32 v13, v13, v14, v16
	v_div_fixup_f32 v6, v13, v12, v6
	ds_write_b32 v3, v6
	v_add_u32_e32 v3, 0x800, v3
	s_andn2_b64 exec, exec, s[4:5]
	s_cbranch_execnz .LBB0_22
	s_or_b64 exec, exec, s[4:5]
	v_readfirstlane_b32 s1, v4
	v_readfirstlane_b32 s0, v2
	s_waitcnt lgkmcnt(0)
	v_writelane_b32 v255, s1, 6
	s_barrier
	v_readlane_b32 s1, v255, 0
	s_cmpk_gt_i32 s1, 0x2885
	s_cbranch_scc1 .LBB0_89
	v_add_u32_e32 v2, 0x200, v190
	v_lshrrev_b32_e32 v76, 6, v2
	v_add_u32_e32 v2, 0x600, v190
	v_lshrrev_b32_e32 v78, 6, v2
	v_add_u32_e32 v2, 0xa00, v190
	v_lshrrev_b32_e32 v80, 6, v2
	v_add_u32_e32 v2, 0xe00, v190
	v_lshrrev_b32_e32 v63, 6, v190
	v_lshrrev_b32_e32 v82, 6, v2
	s_movk_i32 s1, 0x404
	v_mov_b32_e32 v2, 0x4040
	v_mad_u32_u24 v31, v63, s1, v2
	v_mov_b32_e32 v2, 0x8080
	v_mad_u32_u24 v33, v63, s1, v2
	v_mov_b32_e32 v2, 0xc0c0
	v_mad_u32_u24 v35, v63, s1, v2
	v_lshlrev_b32_e32 v2, 3, v190
	v_lshrrev_b32_e32 v83, 3, v190
	v_and_b32_e32 v2, 56, v2
	v_mul_u32_u24_e32 v4, 0x404, v2
	v_lshlrev_b32_e32 v5, 2, v83
	v_add3_u32 v84, 0, v4, v5
	v_and_b32_e32 v4, 15, v190
	v_and_b32_e32 v6, 31, v190
	s_mov_b32 s4, 0xbd000000
	v_cvt_f32_ubyte0_e32 v5, v4
	v_cvt_f32_ubyte0_e32 v4, v6
	s_mov_b32 s5, 0xbd800000
	v_pk_mul_f32 v[4:5], v[4:5], s[4:5]
	v_mov_b32_e32 v20, 0x461c4000
	v_cmp_eq_f32_e32 vcc, 0, v5
	s_mov_b32 s1, 0x3f2aaaab
	v_mov_b32_e32 v22, 0x3e91f4c4
	v_cndmask_b32_e64 v16, v20, 1.0, vcc
	v_frexp_mant_f32_e32 v6, v16
	v_cmp_gt_f32_e64 s[4:5], s1, v6
	s_mov_b32 s2, 0x3f317218
	v_mov_b32_e32 v23, 0x3ecccdef
	v_cndmask_b32_e64 v7, 1.0, 2.0, s[4:5]
	v_mul_f32_e32 v6, v6, v7
	v_add_f32_e32 v9, 1.0, v6
	v_rcp_f32_e32 v14, v9
	v_add_f32_e32 v7, -1.0, v9
	v_sub_f32_e32 v11, v6, v7
	v_add_f32_e32 v7, -1.0, v6
	v_mul_f32_e32 v15, v7, v14
	v_mul_f32_e32 v8, v9, v15
	v_fma_f32 v10, v15, v9, -v8
	v_fmac_f32_e32 v10, v15, v11
	v_add_f32_e32 v6, v8, v10
	v_sub_f32_e32 v9, v7, v6
	v_pk_add_f32 v[12:13], v[6:7], v[8:9] neg_lo:[0,1] neg_hi:[0,1]
	v_mov_b32_e32 v11, v6
	v_pk_add_f32 v[6:7], v[12:13], v[10:11] neg_lo:[0,1] neg_hi:[0,1]
	s_mov_b32 s8, 0x3fb8aa3b
	v_add_f32_e32 v6, v6, v7
	v_add_f32_e32 v6, v9, v6
	v_mul_f32_e32 v7, v14, v6
	v_add_f32_e32 v6, v15, v7
	v_sub_f32_e32 v8, v6, v15
	v_sub_f32_e32 v17, v7, v8
	v_mul_f32_e32 v7, v6, v6
	v_fma_f32 v9, v6, v6, -v7
	v_add_f32_e32 v8, v17, v17
	v_fmac_f32_e32 v9, v6, v8
	v_add_f32_e32 v8, v7, v9
	v_fmamk_f32 v10, v8, 0x3e76c4e1, v22
	v_fmaak_f32 v10, v8, v10, 0x3ecccdef
	v_sub_f32_e32 v7, v8, v7
	v_sub_f32_e32 v18, v9, v7
	v_mul_f32_e32 v7, v8, v10
	v_fma_f32 v9, v8, v10, -v7
	v_fmac_f32_e32 v9, v18, v10
	v_add_f32_e32 v10, v7, v9
	v_add_f32_e32 v11, 0x3f2aaaaa, v10
	v_sub_f32_e32 v7, v10, v7
	v_sub_f32_e32 v7, v9, v7
	v_add_f32_e32 v9, 0xbf2aaaaa, v11
	v_add_f32_e32 v7, 0x31739010, v7
	v_sub_f32_e32 v9, v10, v9
	v_pk_mul_f32 v[12:13], v[6:7], v[8:9]
	v_pk_add_f32 v[14:15], v[6:7], v[8:9]
	v_fma_f32 v10, v8, v6, -v12
	v_fmac_f32_e32 v10, v8, v17
	v_mov_b32_e32 v13, v15
	v_fmac_f32_e32 v10, v18, v6
	v_pk_add_f32 v[8:9], v[12:13], v[10:11]
	v_ldexp_f32 v18, v17, 1
	v_sub_f32_e32 v7, v8, v12
	v_sub_f32_e32 v7, v10, v7
	v_sub_f32_e32 v10, v11, v9
	v_add_f32_e32 v13, v15, v10
	v_pk_mul_f32 v[10:11], v[8:9], v[8:9] op_sel:[0,1] op_sel_hi:[1,0]
	v_cvt_f64_f32_e32 v[14:15], v16
	v_frexp_exp_i32_f64_e32 v11, v[14:15]
	v_subbrev_co_u32_e64 v11, s[4:5], 0, v11, s[4:5]
	v_cvt_f32_i32_e32 v11, v11
	v_fma_f32 v12, v8, v9, -v10
	v_fmac_f32_e32 v12, v8, v13
	v_fmac_f32_e32 v12, v7, v9
	v_mul_f32_e32 v8, 0x3f317218, v11
	v_fma_f32 v14, v11, s2, -v8
	v_fmac_f32_e32 v14, 0xb102e308, v11
	v_ldexp_f32 v15, v6, 1
	v_add_f32_e32 v9, v10, v12
	v_pk_add_f32 v[6:7], v[8:9], v[14:15]
	v_mov_b32_e32 v16, v9
	v_mov_b32_e32 v17, v7
	v_mov_b32_e32 v11, v15
	v_pk_add_f32 v[10:11], v[16:17], v[10:11] neg_lo:[0,1] neg_hi:[0,1]
	v_mov_b32_e32 v13, v9
	v_pk_add_f32 v[10:11], v[12:13], v[10:11] neg_lo:[0,1] neg_hi:[0,1]
	v_mov_b32_e32 v15, v6
	v_add_f32_e32 v9, v18, v10
	v_add_f32_e32 v9, v9, v11
	v_pk_add_f32 v[10:11], v[6:7], v[8:9] neg_lo:[0,1] neg_hi:[0,1]
	v_pk_add_f32 v[12:13], v[6:7], v[8:9]
	v_mov_b32_e32 v8, v9
	v_mov_b32_e32 v11, v13
	v_pk_add_f32 v[16:17], v[14:15], v[10:11] neg_lo:[0,1] neg_hi:[0,1]
	v_pk_add_f32 v[10:11], v[14:15], v[10:11]
	v_mov_b32_e32 v9, v6
	v_pk_add_f32 v[14:15], v[10:11], v[6:7] op_sel:[1,0] op_sel_hi:[0,1] neg_lo:[0,1] neg_hi:[0,1]
	v_pk_add_f32 v[18:19], v[12:13], v[14:15] op_sel_hi:[1,0] neg_lo:[0,1] neg_hi:[0,1]
	v_mov_b32_e32 v10, v13
	v_pk_mov_b32 v[12:13], v[6:7], v[14:15] op_sel:[1,0]
	v_mov_b32_e32 v18, v16
	v_pk_add_f32 v[12:13], v[10:11], v[12:13] neg_lo:[0,1] neg_hi:[0,1]
	v_cmp_eq_f32_e64 s[4:5], 0, v4
	v_pk_add_f32 v[6:7], v[8:9], v[12:13] neg_lo:[0,1] neg_hi:[0,1]
	v_mov_b32_e32 v17, v11
	v_pk_add_f32 v[8:9], v[18:19], v[6:7]
	v_cndmask_b32_e64 v7, v20, 1.0, s[4:5]
	v_frexp_mant_f32_e32 v10, v7
	v_cmp_gt_f32_e64 s[6:7], s1, v10
	s_mov_b32 s1, 0x7f800000
	s_mov_b32 s9, 0xc2ce8ed0
	v_cndmask_b32_e64 v12, 1.0, 2.0, s[6:7]
	v_mul_f32_e32 v10, v10, v12
	v_add_f32_e32 v12, 1.0, v10
	v_rcp_f32_e32 v24, v12
	v_add_f32_e32 v13, -1.0, v12
	v_sub_f32_e32 v15, v10, v13
	v_add_f32_e32 v13, -1.0, v10
	v_mul_f32_e32 v10, v13, v24
	v_mul_f32_e32 v14, v12, v10
	v_fma_f32 v18, v10, v12, -v14
	v_fmac_f32_e32 v18, v10, v15
	v_add_f32_e32 v12, v14, v18
	v_sub_f32_e32 v15, v13, v12
	v_pk_add_f32 v[20:21], v[12:13], v[14:15] neg_lo:[0,1] neg_hi:[0,1]
	v_mov_b32_e32 v19, v12
	v_pk_add_f32 v[12:13], v[20:21], v[18:19] neg_lo:[0,1] neg_hi:[0,1]
	s_movk_i32 s10, 0x204
	v_add_f32_e32 v12, v12, v13
	v_add_f32_e32 v12, v15, v12
	v_mul_f32_e32 v13, v24, v12
	v_add_f32_e32 v12, v10, v13
	v_sub_f32_e32 v10, v12, v10
	v_sub_f32_e32 v10, v13, v10
	v_mul_f32_e32 v13, v12, v12
	v_fma_f32 v15, v12, v12, -v13
	v_add_f32_e32 v14, v10, v10
	v_fmac_f32_e32 v15, v12, v14
	v_add_f32_e32 v14, v13, v15
	v_fmac_f32_e32 v22, 0x3e76c4e1, v14
	v_fmac_f32_e32 v23, v14, v22
	v_sub_f32_e32 v13, v14, v13
	v_sub_f32_e32 v24, v15, v13
	v_mul_f32_e32 v13, v14, v23
	v_fma_f32 v15, v14, v23, -v13
	v_fmac_f32_e32 v15, v24, v23
	v_add_f32_e32 v18, v13, v15
	v_add_f32_e32 v19, 0x3f2aaaaa, v18
	v_sub_f32_e32 v13, v18, v13
	v_sub_f32_e32 v13, v15, v13
	v_add_f32_e32 v15, 0xbf2aaaaa, v19
	v_add_f32_e32 v13, 0x31739010, v13
	v_sub_f32_e32 v15, v18, v15
	v_pk_mul_f32 v[20:21], v[12:13], v[14:15]
	v_pk_add_f32 v[22:23], v[12:13], v[14:15]
	v_fma_f32 v18, v14, v12, -v20
	v_fmac_f32_e32 v18, v14, v10
	v_mov_b32_e32 v21, v23
	v_fmac_f32_e32 v18, v24, v12
	v_pk_add_f32 v[14:15], v[20:21], v[18:19]
	v_and_b32_e32 v62, 0xfc, v1
	v_sub_f32_e32 v13, v14, v20
	v_cvt_f64_f32_e32 v[20:21], v7
	v_frexp_exp_i32_f64_e32 v7, v[20:21]
	v_subbrev_co_u32_e64 v7, s[6:7], 0, v7, s[6:7]
	v_cvt_f32_i32_e32 v7, v7
	v_sub_f32_e32 v13, v18, v13
	v_sub_f32_e32 v18, v19, v15
	v_add_f32_e32 v22, v23, v18
	v_pk_mul_f32 v[18:19], v[14:15], v[14:15] op_sel:[0,1] op_sel_hi:[1,0]
	v_ldexp_f32 v23, v12, 1
	v_fma_f32 v20, v14, v15, -v18
	v_fmac_f32_e32 v20, v14, v22
	v_mul_f32_e32 v14, 0x3f317218, v7
	v_fmac_f32_e32 v20, v13, v15
	v_fma_f32 v22, v7, s2, -v14
	v_fmac_f32_e32 v22, 0xb102e308, v7
	v_add_f32_e32 v15, v18, v20
	v_pk_add_f32 v[12:13], v[14:15], v[22:23]
	v_mov_b32_e32 v24, v15
	v_mov_b32_e32 v25, v13
	v_mov_b32_e32 v19, v23
	v_pk_add_f32 v[18:19], v[24:25], v[18:19] neg_lo:[0,1] neg_hi:[0,1]
	v_mov_b32_e32 v21, v15
	v_ldexp_f32 v7, v10, 1
	v_pk_add_f32 v[18:19], v[20:21], v[18:19] neg_lo:[0,1] neg_hi:[0,1]
	v_mov_b32_e32 v23, v12
	v_add_f32_e32 v7, v7, v18
	v_add_f32_e32 v15, v7, v19
	v_pk_add_f32 v[18:19], v[12:13], v[14:15] neg_lo:[0,1] neg_hi:[0,1]
	v_pk_add_f32 v[20:21], v[12:13], v[14:15]
	v_mov_b32_e32 v14, v15
	v_mov_b32_e32 v19, v21
	v_pk_add_f32 v[24:25], v[22:23], v[18:19] neg_lo:[0,1] neg_hi:[0,1]
	v_pk_add_f32 v[18:19], v[22:23], v[18:19]
	v_mov_b32_e32 v15, v12
	v_pk_add_f32 v[22:23], v[18:19], v[12:13] op_sel:[1,0] op_sel_hi:[0,1] neg_lo:[0,1] neg_hi:[0,1]
	v_pk_add_f32 v[26:27], v[20:21], v[22:23] op_sel_hi:[1,0] neg_lo:[0,1] neg_hi:[0,1]
	v_mov_b32_e32 v18, v21
	v_pk_mov_b32 v[20:21], v[12:13], v[22:23] op_sel:[1,0]
	v_mov_b32_e32 v26, v24
	v_pk_add_f32 v[20:21], v[18:19], v[20:21] neg_lo:[0,1] neg_hi:[0,1]
	v_mov_b32_e32 v23, v9
	v_pk_add_f32 v[12:13], v[14:15], v[20:21] neg_lo:[0,1] neg_hi:[0,1]
	v_mov_b32_e32 v21, v8
	v_pk_add_f32 v[14:15], v[26:27], v[12:13]
	v_mov_b32_e32 v10, v19
	v_mov_b32_e32 v20, v14
	v_mov_b32_e32 v22, v15
	v_pk_add_f32 v[22:23], v[20:21], v[22:23]
	v_mov_b32_e32 v25, v19
	v_pk_add_f32 v[10:11], v[10:11], v[22:23]
	v_mov_b32_e32 v7, v23
	v_mov_b32_e32 v9, v11
	v_mov_b32_e32 v15, v10
	v_pk_add_f32 v[8:9], v[8:9], v[16:17] neg_lo:[0,1] neg_hi:[0,1]
	v_pk_add_f32 v[14:15], v[14:15], v[24:25] neg_lo:[0,1] neg_hi:[0,1]
	v_mov_b32_e32 v19, v8
	v_mov_b32_e32 v18, v14
	v_mov_b32_e32 v13, v22
	v_pk_add_f32 v[6:7], v[6:7], v[8:9] neg_lo:[0,1] neg_hi:[0,1]
	v_pk_add_f32 v[8:9], v[20:21], v[18:19] neg_lo:[0,1] neg_hi:[0,1]
	v_mov_b32_e32 v25, v16
	v_pk_add_f32 v[12:13], v[12:13], v[14:15] neg_lo:[0,1] neg_hi:[0,1]
	v_pk_add_f32 v[8:9], v[24:25], v[8:9] neg_lo:[0,1] neg_hi:[0,1]
	v_mov_b32_e32 v14, v12
	v_mov_b32_e32 v15, v6
	v_pk_add_f32 v[8:9], v[14:15], v[8:9]
	v_mov_b32_e32 v6, v13
	v_pk_add_f32 v[6:7], v[8:9], v[6:7]
	s_mov_b32 s2, 0x42b17218
	v_pk_add_f32 v[8:9], v[10:11], v[6:7]
	v_lshlrev_b32_e32 v28, 2, v62
	v_pk_add_f32 v[10:11], v[8:9], v[10:11] neg_lo:[0,1] neg_hi:[0,1]
	v_lshl_add_u32 v89, v63, 10, 0
	v_pk_add_f32 v[6:7], v[6:7], v[10:11] neg_lo:[0,1] neg_hi:[0,1]
	v_pk_mul_f32 v[10:11], v[4:5], v[8:9]
	v_mov_b32_e32 v65, 0
	v_pk_fma_f32 v[8:9], v[4:5], v[8:9], v[10:11] neg_lo:[0,0,1] neg_hi:[0,0,1]
	v_add_u32_e32 v3, 0, v28
	v_pk_fma_f32 v[6:7], v[4:5], v[6:7], v[8:9]
	v_mul_u32_u24_e32 v29, 0x404, v63
	v_pk_add_f32 v[8:9], v[10:11], v[6:7]
	v_mul_u32_u24_e32 v30, 0x404, v76
	v_pk_add_f32 v[12:13], v[8:9], v[10:11] neg_lo:[0,1] neg_hi:[0,1]
	v_mul_u32_u24_e32 v32, 0x404, v78
	v_pk_add_f32 v[6:7], v[6:7], v[12:13] neg_lo:[0,1] neg_hi:[0,1]
	v_mov_b32_e32 v12, 0x204
	v_cmp_class_f32_e64 s[6:7], v10, v12
	v_mul_u32_u24_e32 v34, 0x404, v80
	v_mul_u32_u24_e32 v36, 0x404, v82
	v_cndmask_b32_e64 v8, v8, v10, s[6:7]
	v_cmp_class_f32_e64 s[6:7], v11, v12
	v_mov_b32_e32 v10, 0x37000000
	s_add_u32 s46, s36, 0x2dc48000
	v_cndmask_b32_e64 v9, v9, v11, s[6:7]
	v_cmp_eq_f32_e64 s[6:7], s2, v9
	v_or_b32_e32 v77, 16, v63
	v_or_b32_e32 v79, 32, v63
	v_cndmask_b32_e64 v11, 0, v10, s[6:7]
	v_sub_f32_e32 v12, v9, v11
	v_mul_f32_e32 v13, 0x3fb8aa3b, v12
	v_fma_f32 v14, v12, s8, -v13
	v_rndne_f32_e32 v15, v13
	v_fmac_f32_e32 v14, 0x32a5705f, v12
	v_sub_f32_e32 v13, v13, v15
	v_add_f32_e32 v13, v13, v14
	v_exp_f32_e32 v13, v13
	v_cvt_i32_f32_e32 v14, v15
	v_cmp_neq_f32_e64 s[6:7], |v9|, s1
	v_or_b32_e32 v81, 48, v63
	s_mov_b32 s41, 0
	v_cndmask_b32_e64 v7, 0, v7, s[6:7]
	v_ldexp_f32 v9, v13, v14
	v_cmp_ngt_f32_e64 s[6:7], s9, v12
	v_add_f32_e32 v7, v11, v7
	v_mov_b32_e32 v11, 0x7f800000
	v_cndmask_b32_e64 v9, 0, v9, s[6:7]
	v_cmp_nlt_f32_e64 s[6:7], s2, v12
	v_or_b32_e32 v85, 0x80, v83
	v_or_b32_e32 v86, 0xffff4000, v190
	v_cndmask_b32_e64 v9, v11, v9, s[6:7]
	v_fma_f32 v7, v9, v7, v9
	v_cmp_class_f32_e64 s[6:7], v9, s10
	v_lshlrev_b32_e32 v66, 8, v63
	v_mov_b32_e32 v67, v65
	v_cndmask_b32_e64 v7, v7, v9, s[6:7]
	v_cmp_neq_f32_e64 s[6:7], v5, |v5|
	s_addc_u32 s47, s37, 0
	v_add_u32_e32 v91, 0xfffffe00, v190
	v_cndmask_b32_e64 v9, v11, 0, s[6:7]
	v_cndmask_b32_e64 v9, v9, 1.0, vcc
	v_cmp_eq_f32_e32 vcc, s2, v8
	v_cmp_class_f32_e64 s[6:7], v5, s10
	s_mov_b32 s33, 0xf400000
	v_cndmask_b32_e32 v5, 0, v10, vcc
	v_cndmask_b32_e64 v87, |v7|, v9, s[6:7]
	v_sub_f32_e32 v7, v8, v5
	v_mul_f32_e32 v9, 0x3fb8aa3b, v7
	v_fma_f32 v10, v7, s8, -v9
	v_rndne_f32_e32 v12, v9
	v_fmac_f32_e32 v10, 0x32a5705f, v7
	v_sub_f32_e32 v9, v9, v12
	v_add_f32_e32 v9, v9, v10
	v_exp_f32_e32 v9, v9
	v_cvt_i32_f32_e32 v10, v12
	v_cmp_neq_f32_e64 vcc, |v8|, s1
	v_cmp_neq_f32_e64 s[6:7], v4, |v4|
	s_movk_i32 s1, 0x300
	v_cndmask_b32_e32 v6, 0, v6, vcc
	v_add_f32_e32 v5, v5, v6
	v_ldexp_f32 v6, v9, v10
	v_cmp_ngt_f32_e32 vcc, s9, v7
	s_mov_b32 s8, 0x31850000
	s_mov_b32 s9, 0x30bd0000
	v_cndmask_b32_e32 v6, 0, v6, vcc
	v_cmp_nlt_f32_e32 vcc, s2, v7
	s_mov_b32 s2, 0xc000
	s_mov_b32 s54, 0xb400000
	v_cndmask_b32_e32 v6, v11, v6, vcc
	v_fma_f32 v5, v6, v5, v6
	v_cmp_class_f32_e64 vcc, v6, s10
	s_mov_b32 s55, 0x8c00000
	s_movk_i32 s56, 0xa8
	v_cndmask_b32_e32 v5, v5, v6, vcc
	v_cndmask_b32_e64 v6, v11, 0, s[6:7]
	v_readlane_b32 s6, v255, 1
	v_cndmask_b32_e64 v6, v6, 1.0, s[4:5]
	v_cmp_class_f32_e64 s[4:5], v4, s10
	v_lshlrev_b32_e32 v4, 11, v63
	v_readlane_b32 s7, v255, 2
	v_cndmask_b32_e64 v88, |v5|, v6, s[4:5]
	v_add3_u32 v90, v89, v4, v28
	s_load_dwordx8 s[16:23], s[6:7], 0x10
	s_load_dwordx2 s[42:43], s[6:7], 0xc8
	s_load_dwordx4 s[24:27], s[6:7], 0xb8
	s_load_dwordx4 s[28:31], s[6:7], 0x40
	s_load_dwordx2 s[44:45], s[6:7], 0x60
	v_lshrrev_b32_e32 v4, 8, v190
	v_mov_b32_e32 v6, 2
	v_mul_hi_u32_u24_e32 v5, 0xc000, v4
	v_mul_u32_u24_e32 v4, 0xc000, v4
	v_lshlrev_b32_sdwa v6, v6, v190 dst_sel:DWORD dst_unused:UNUSED_PAD src0_sel:DWORD src1_sel:BYTE_0
	v_or_b32_e32 v4, v4, v6
	v_lshl_add_u64 v[4:5], s[36:37], 0, v[4:5]
	s_mov_b64 s[6:7], 0x2dc00000
	v_lshl_add_u64 v[68:69], v[4:5], 0, s[6:7]
	s_movk_i32 s6, 0xc00
	v_and_or_b32 v4, v1, s6, v6
	v_add_u32_e32 v4, 0, v4
	v_cmp_gt_u32_e64 s[4:5], s1, v190
	s_movk_i32 s1, 0xff
	v_add_u32_e32 v92, 0x6000, v4
	s_mov_b32 s57, 0x7800000
	v_add_u32_e32 v93, v3, v29
	v_add_u32_e32 v94, v3, v30
	v_add_u32_e32 v95, v3, v31
	v_add_u32_e32 v96, v3, v32
	v_add_u32_e32 v97, v3, v33
	v_add_u32_e32 v98, v3, v34
	v_add_u32_e32 v99, v3, v35
	v_add_u32_e32 v100, v3, v36
	v_lshlrev_b32_e32 v70, 1, v2
	s_mov_b32 s58, 0x2ff50000
	s_mov_b32 s59, 0x2f2d0000
	s_movk_i32 s60, 0x7ff
	s_brev_b32 s61, 18
	s_mov_b32 s62, 0xfe5163ab
	s_mov_b32 s63, 0x3c439041
	s_mov_b32 s64, 0xdb629599
	s_mov_b32 s65, 0xf534ddc0
	s_mov_b32 s66, 0xfc2757d1
	s_mov_b32 s67, 0x4e441529
	s_mov_b32 s68, 0xa2f9836e
	s_mov_b32 s69, 0x3fc90fda
	s_mov_b32 s70, 0x3f22f983
	s_mov_b32 s71, 0xbfc90fda
	v_mov_b32_e32 v101, 0x3c0881c4
	v_mov_b32_e32 v102, 0xbab64f3b
	s_brev_b32 s72, 1
	s_movk_i32 s73, 0x1f8
	s_mov_b32 s74, 0x18000
	s_mov_b32 s75, 0x24000
	s_mov_b32 s76, 0x30000
	s_mov_b32 s77, 0x3c000
	s_mov_b32 s78, 0x48000
	s_mov_b32 s79, 0x54000
	s_mov_b32 s80, 0x60000
	s_mov_b32 s81, 0x6c000
	s_mov_b32 s82, 0x78000
	s_mov_b32 s83, 0x84000
	s_mov_b32 s84, 0x90000
	s_mov_b32 s85, 0x9c000
	s_mov_b32 s86, 0xa8000
	s_mov_b32 s87, 0xb4000
	s_mov_b64 s[48:49], 0x18000
	v_not_b32_e32 v103, 63
	v_not_b32_e32 v104, 31
	v_mov_b32_e32 v105, 0x7fc00000
	v_readlane_b32 s88, v255, 0
	s_mov_b32 s32, 0
	s_movk_i32 s90, 0x2886
	s_cmpk_eq_i32 s3, 0x100
	s_cselect_b32 s93, 1, 0
	s_cmpk_lt_i32 s88, 96
	s_cselect_b32 s94, 1, 0
	s_and_b32 s94, s94, s93
	s_cmp_eq_u32 s94, 1
	s_cselect_b32 s90, 8192, s90
	s_branch .LBB0_27

.Lprep_left_item:
	s_cmpk_lt_i32 s89, 864
	s_cbranch_scc0 .LBB0_89
	s_mul_i32 s91, s89, 0x2ab
	s_lshr_b32 s91, s91, 16
	s_mul_i32 s92, s91, 96
	s_sub_i32 s92, s89, s92
	s_add_i32 s91, s91, 32
	s_lshl_b32 s91, s91, 8
	s_add_i32 s88, s91, s92
